# v12 + row-sum fillers as v_add_f32 (not packed) + loop-top K/V tile loads with scalar-advanced bases, always-valid chunks issued unconditionally
# speedup vs baseline: 1.0306x; 1.0090x over previous
.LBB0_1312:
	v_pk_add_f32 v[66:67], v[154:155], 0 op_sel_hi:[1,0]
	s_sub_i32 s33, 0x1000, s53
	v_pk_add_f32 v[66:67], v[168:169], v[66:67]
	s_lshr_b32 s53, s33, 6
	v_pk_add_f32 v[66:67], v[170:171], v[66:67]
	s_mul_hi_u32 s33, s84, 0x15555556
	v_pk_add_f32 v[66:67], v[172:173], v[66:67]
	s_lshl_b32 s49, s54, 7
	v_pk_add_f32 v[66:67], v[174:175], v[66:67]
	s_or_b32 s54, s48, 31
	v_pk_add_f32 v[66:67], v[176:177], v[66:67]
	s_lshl_b32 s55, s55, 10
	v_pk_add_f32 v[66:67], v[178:179], v[66:67]
	s_lshl_b32 s82, s82, 10
	v_pk_add_f32 v[66:67], v[180:181], v[66:67]
	s_lshl_b32 s33, s33, 13
	v_pk_add_f32 v[66:67], v[182:183], v[66:67]
	s_add_u32 s33, s87, s33
	v_pk_add_f32 v[66:67], v[184:185], v[66:67]
	s_addc_u32 s84, 0, 0
	v_pk_add_f32 v[66:67], v[186:187], v[66:67]
	s_add_u32 s90, s33, 0x11804100
	v_pk_add_f32 v[66:67], v[188:189], v[66:67]
	s_addc_u32 s91, s84, 0
	v_pk_add_f32 v[66:67], v[190:191], v[66:67]
	s_add_u32 s33, s86, s85
	v_pk_add_f32 v[66:67], v[192:193], v[66:67]
	s_addc_u32 s85, 0, 0
	v_pk_add_f32 v[66:67], v[194:195], v[66:67]
	s_add_u32 s84, s33, 0x19094000
	v_pk_add_f32 v[66:67], v[196:197], v[66:67]
	v_mov_b32_e32 v161, v145
	v_add_f32_e32 v65, v66, v67
	v_mov_b32_e32 v163, v145
	v_mov_b32_e32 v165, v145
	v_mov_b32_e32 v167, v145
	v_mov_b32_e32 v157, v145
	v_mov_b32_e32 v159, v145
	s_addc_u32 s85, s85, 0
	v_add_f32_e32 v184, v64, v65
	v_lshl_add_u64 v[154:155], s[90:91], 0, v[144:145]
	v_lshl_add_u64 v[156:157], s[90:91], 0, v[156:157]
	v_lshl_add_u64 v[158:159], s[90:91], 0, v[158:159]
	v_lshl_add_u64 v[160:161], s[84:85], 0, v[160:161]
	v_lshl_add_u64 v[162:163], s[84:85], 0, v[162:163]
	v_lshl_add_u64 v[164:165], s[84:85], 0, v[164:165]
	v_lshl_add_u64 v[166:167], s[84:85], 0, v[166:167]
	s_mov_b32 s87, 0
	s_movk_i32 s84, 0x7f
	s_mov_b32 s85, 1
	v_mov_b32_e32 v216, v92
	v_mov_b32_e32 v217, v93
	v_mov_b32_e32 v218, v94
	v_mov_b32_e32 v219, v95
	v_mov_b32_e32 v220, v88
	v_mov_b32_e32 v221, v89
	v_mov_b32_e32 v222, v90
	v_mov_b32_e32 v223, v91
	v_mov_b32_e32 v224, v84
	v_mov_b32_e32 v225, v85
	v_mov_b32_e32 v226, v86
	v_mov_b32_e32 v227, v87
	v_mov_b32_e32 v228, v80
	v_mov_b32_e32 v229, v81
	v_mov_b32_e32 v230, v82
	v_mov_b32_e32 v231, v83
	v_mov_b32_e32 v194, 0
	v_mov_b32_e32 v195, 0
	v_mov_b32_e32 v196, 0
	v_mov_b32_e32 v197, 0
	s_mov_b64 s[92:93], s[42:43]
	s_mov_b64 s[94:95], s[42:43]
.LBB0_1313:
	s_and_b32 s89, s85, 1
	s_add_i32 s33, s52, 1
	s_waitcnt vmcnt(0)
	s_cmp_lg_u32 s52, 2
	s_mov_b32 s86, s52
	s_cselect_b32 s52, s33, 0
	s_add_i32 s85, s85, 1
	s_cmp_ge_u32 s85, s53
	s_waitcnt vmcnt(0)
	s_barrier
	s_cbranch_scc1 .LBB0_1322
	s_xor_b32 s33, s89, 1
	s_mulk_i32 s33, 0x6400
	s_add_i32 m0, s33, s51
	s_nop 0
	global_load_lds_dwordx4 v160, s[92:93]
	s_add_i32 m0, s33, s55
	s_nop 0
	global_load_lds_dwordx4 v162, s[92:93]
	s_add_i32 m0, s33, s82
	s_nop 0
	global_load_lds_dwordx4 v164, s[92:93]
	s_and_b64 vcc, exec, s[10:11]
	s_cbranch_vccnz .Lfa_k3done
	s_add_i32 m0, s33, 0x6000
	s_nop 0
	global_load_lds_dwordx4 v166, s[92:93]
.Lfa_k3done:
	s_mul_i32 s33, s52, 0x4800
	s_add_i32 s90, s33, s51
	s_add_i32 m0, s90, 0xc800
	s_nop 0
	global_load_lds_dwordx4 v154, s[94:95]
	s_add_i32 s90, s33, s55
	s_add_i32 m0, s90, 0xc800
	s_nop 0
	global_load_lds_dwordx4 v156, s[94:95]
	s_and_b64 vcc, exec, s[16:17]
	s_cbranch_vccnz .LBB0_1322
	s_add_i32 s90, s33, s82
	s_add_i32 m0, s90, 0xc800
	s_nop 0
	global_load_lds_dwordx4 v158, s[94:95]

.LBB0_1327:
	v_max_f32_e32 v144, v81, v81
	v_max_f32_e32 v168, v80, v80
	v_max_f32_e32 v144, v168, v144
	v_max3_f32 v144, v144, v82, v83
	v_max3_f32 v144, v144, v84, v85
	v_max3_f32 v144, v144, v86, v87
	v_max3_f32 v144, v144, v88, v89
	v_max3_f32 v144, v144, v90, v91
	v_max3_f32 v144, v144, v92, v93
	v_max3_f32 v144, v144, v94, v95
	s_nop 0
	v_max3_f32 v144, v144, v64, v65
	v_max3_f32 v144, v144, v66, v67
	v_max3_f32 v144, v144, v68, v69
	v_max3_f32 v144, v144, v70, v71
	v_max3_f32 v144, v144, v72, v73
	v_max3_f32 v144, v144, v74, v75
	v_max3_f32 v144, v144, v76, v77
	v_max3_f32 v144, v144, v78, v79
	ds_bpermute_b32 v168, v241, v144
	s_waitcnt lgkmcnt(0)
	v_max_f32_e32 v168, v168, v168
	v_max_f32_e32 v144, v144, v168
	v_cmp_lt_f32_e32 vcc, s79, v144
	s_cbranch_vccnz .Lfa_rare
	s_mul_i32 s33, s87, 0x4800
	v_add_u32_e32 v243, s33, v151
	ds_read_b128 v[232:235], v243 offset:51200
	ds_read_b128 v[202:205], v243 offset:55808
	ds_read_b128 v[206:209], v243 offset:60416
	ds_read_b128 v[244:247], v243 offset:65024
	s_waitcnt lgkmcnt(3)
	v_mfma_f32_32x32x16_bf16 v[48:63], v[232:235], v[216:219], v[48:63]
	ds_read_b128 v[232:235], v243 offset:51232
	v_exp_f32_e32 v168, v80
	v_exp_f32_e32 v169, v81
	s_waitcnt lgkmcnt(3)
	v_mfma_f32_32x32x16_bf16 v[32:47], v[202:205], v[216:219], v[32:47]
	ds_read_b128 v[202:205], v243 offset:55840
	v_exp_f32_e32 v170, v82
	v_exp_f32_e32 v171, v83
	s_waitcnt lgkmcnt(3)
	v_mfma_f32_32x32x16_bf16 v[16:31], v[206:209], v[216:219], v[16:31]
	ds_read_b128 v[206:209], v243 offset:60448
	v_exp_f32_e32 v172, v84
	v_exp_f32_e32 v173, v85
	s_waitcnt lgkmcnt(3)
	v_mfma_f32_32x32x16_bf16 v[0:15], v[244:247], v[216:219], v[0:15]
	ds_read_b128 v[244:247], v243 offset:65056
	v_exp_f32_e32 v174, v86
	v_exp_f32_e32 v175, v87
	s_waitcnt lgkmcnt(3)
	v_mfma_f32_32x32x16_bf16 v[48:63], v[232:235], v[220:223], v[48:63]
	ds_read_b128 v[232:235], v243 offset:51264
	v_exp_f32_e32 v176, v88
	v_exp_f32_e32 v177, v89
	v_cvt_pk_bf16_f32 v216, v168, v169
	v_add_f32_e32 v194, v194, v168
	v_add_f32_e32 v195, v195, v169
	s_waitcnt lgkmcnt(3)
	v_mfma_f32_32x32x16_bf16 v[32:47], v[202:205], v[220:223], v[32:47]
	ds_read_b128 v[202:205], v243 offset:55872
	v_exp_f32_e32 v178, v90
	v_exp_f32_e32 v179, v91
	v_cvt_pk_bf16_f32 v217, v170, v171
	v_add_f32_e32 v196, v196, v170
	v_add_f32_e32 v197, v197, v171
	s_waitcnt lgkmcnt(3)
	v_mfma_f32_32x32x16_bf16 v[16:31], v[206:209], v[220:223], v[16:31]
	ds_read_b128 v[206:209], v243 offset:60480
	v_exp_f32_e32 v180, v92
	v_exp_f32_e32 v181, v93
	v_cvt_pk_bf16_f32 v218, v172, v173
	v_add_f32_e32 v194, v194, v172
	v_add_f32_e32 v195, v195, v173
	s_waitcnt lgkmcnt(3)
	v_mfma_f32_32x32x16_bf16 v[0:15], v[244:247], v[220:223], v[0:15]
	ds_read_b128 v[244:247], v243 offset:65088
	v_exp_f32_e32 v182, v94
	v_exp_f32_e32 v183, v95
	v_cvt_pk_bf16_f32 v219, v174, v175
	v_add_f32_e32 v196, v196, v174
	v_add_f32_e32 v197, v197, v175
	s_waitcnt lgkmcnt(3)
	v_mfma_f32_32x32x16_bf16 v[48:63], v[232:235], v[224:227], v[48:63]
	ds_read_b128 v[232:235], v243 offset:51296
	v_exp_f32_e32 v64, v64
	v_exp_f32_e32 v65, v65
	v_cvt_pk_bf16_f32 v220, v176, v177
	v_add_f32_e32 v194, v194, v176
	v_add_f32_e32 v195, v195, v177
	s_waitcnt lgkmcnt(3)
	v_mfma_f32_32x32x16_bf16 v[32:47], v[202:205], v[224:227], v[32:47]
	ds_read_b128 v[202:205], v243 offset:55904
	v_exp_f32_e32 v66, v66
	v_exp_f32_e32 v67, v67
	v_cvt_pk_bf16_f32 v221, v178, v179
	v_add_f32_e32 v196, v196, v178
	v_add_f32_e32 v197, v197, v179
	s_waitcnt lgkmcnt(3)
	v_mfma_f32_32x32x16_bf16 v[16:31], v[206:209], v[224:227], v[16:31]
	ds_read_b128 v[206:209], v243 offset:60512
	v_exp_f32_e32 v68, v68
	v_exp_f32_e32 v69, v69
	v_cvt_pk_bf16_f32 v222, v180, v181
	v_add_f32_e32 v194, v194, v180
	v_add_f32_e32 v195, v195, v181
	s_waitcnt lgkmcnt(3)
	v_mfma_f32_32x32x16_bf16 v[0:15], v[244:247], v[224:227], v[0:15]
	ds_read_b128 v[244:247], v243 offset:65120
	v_exp_f32_e32 v70, v70
	v_exp_f32_e32 v71, v71
	v_cvt_pk_bf16_f32 v223, v182, v183
	v_add_f32_e32 v196, v196, v182
	v_add_f32_e32 v197, v197, v183
	s_waitcnt lgkmcnt(3)
	v_mfma_f32_32x32x16_bf16 v[48:63], v[232:235], v[228:231], v[48:63]
	v_exp_f32_e32 v72, v72
	v_exp_f32_e32 v73, v73
	v_cvt_pk_bf16_f32 v224, v64, v65
	v_add_f32_e32 v194, v194, v64
	v_add_f32_e32 v195, v195, v65
	s_waitcnt lgkmcnt(2)
	v_mfma_f32_32x32x16_bf16 v[32:47], v[202:205], v[228:231], v[32:47]
	v_exp_f32_e32 v74, v74
	v_exp_f32_e32 v75, v75
	v_cvt_pk_bf16_f32 v225, v66, v67
	v_add_f32_e32 v196, v196, v66
	v_add_f32_e32 v197, v197, v67
	s_waitcnt lgkmcnt(1)
	v_mfma_f32_32x32x16_bf16 v[16:31], v[206:209], v[228:231], v[16:31]
	v_exp_f32_e32 v76, v76
	v_exp_f32_e32 v77, v77
	v_cvt_pk_bf16_f32 v226, v68, v69
	v_add_f32_e32 v194, v194, v68
	v_add_f32_e32 v195, v195, v69
	s_waitcnt lgkmcnt(0)
	v_mfma_f32_32x32x16_bf16 v[0:15], v[244:247], v[228:231], v[0:15]
	v_exp_f32_e32 v78, v78
	v_exp_f32_e32 v79, v79
	v_cvt_pk_bf16_f32 v227, v70, v71
	v_add_f32_e32 v196, v196, v70
	v_add_f32_e32 v197, v197, v71
	v_cvt_pk_bf16_f32 v228, v72, v73
	v_add_f32_e32 v194, v194, v72
	v_add_f32_e32 v195, v195, v73
	v_cvt_pk_bf16_f32 v229, v74, v75
	v_add_f32_e32 v196, v196, v74
	v_add_f32_e32 v197, v197, v75
	v_cvt_pk_bf16_f32 v230, v76, v77
	v_add_f32_e32 v194, v194, v76
	v_add_f32_e32 v195, v195, v77
	v_cvt_pk_bf16_f32 v231, v78, v79
	v_add_f32_e32 v196, v196, v78
	v_add_f32_e32 v197, v197, v79
	s_mov_b32 s88, 1
	s_branch .LBB0_1332

.LBB0_1332:
	s_add_i32 s84, s84, 64
	s_add_u32 s92, s92, s36
	s_addc_u32 s93, s93, s37
	s_add_u32 s94, s94, s26
	s_addc_u32 s95, s95, s27
	s_cmp_eq_u32 s53, s85
	s_cbranch_scc1 .LBB0_1340
	s_mov_b32 s87, s86
	s_branch .LBB0_1313
